# post_scan row pass and mLSTM output: remaining IEEE f32 divisions (sigmoid, 1/den) as v_rcp_f32
# baseline (speedup 1.0000x reference)
; DI unsigned pack2(float a, float b) { f32x2_t v = {a, b}; bf16x2_t r = __builtin_convertvector(v, bf16x2_t); return __builtin_bit_cast(unsigned, r); }
; DI float lo16(unsigned u) { return __uint_as_float(u << 16); }
; DI float hi16(unsigned u) { return __uint_as_float(u & 0xffff0000u); }
; DI float sigmoidf_(float x) { return 1.f / (1.f + __expf(-x)); }
; DI void post_scan(const PX& p, int l, int M, unsigned char* smem) {
;     ...
;   for (int r = wg; r < M; r += nw) {
;     const size_t ro = (size_t)r * 768 + lane * 12;
;     {
;       float x[12];
;       const uint2* hf = (const uint2*)(Hf + ro);
;       const uint2* hb = (const uint2*)(Hb + ro);
;       float s = 0.f;
; #pragma unroll
;       for (int i = 0; i < 3; i++) {
;         const uint2 a = hf[i], bq = hb[i];
;         x[4 * i] = lo16(a.x) + lo16(bq.x); x[4 * i + 1] = hi16(a.x) + hi16(bq.x);
;         x[4 * i + 2] = lo16(a.y) + lo16(bq.y); x[4 * i + 3] = hi16(a.y) + hi16(bq.y);
;         s += x[4 * i] + x[4 * i + 1] + x[4 * i + 2] + x[4 * i + 3];
;       }
; #pragma unroll
;       for (int o = 8; o >= 1; o >>= 1) s += __shfl_xor(s, o);
;       const float mu = s * (1.f / 192.f);
;       float q = 0.f;
; #pragma unroll
;       for (int i = 0; i < 12; i++) { x[i] -= mu; q += x[i] * x[i]; }
; #pragma unroll
;       for (int o = 8; o >= 1; o >>= 1) q += __shfl_xor(q, o);
;       const float rs = rsqrtf(q * (1.f / 192.f) + 1e-5f);
;       const uint2* og = (const uint2*)(Zml + (size_t)r * 3072 + 2304 + lane * 12);
;       const float4* gg = (const float4*)(ng + lane * 12);
; #pragma unroll
;       for (int i = 0; i < 3; i++) {
;         const uint2 o = og[i];
;         const float4 g4 = ngv[i];
;         uint2 w_;
;         w_.x = pack2(x[4 * i] * rs * g4.x * sigmoidf_(lo16(o.x)), x[4 * i + 1] * rs * g4.y * sigmoidf_(hi16(o.x)));
;         w_.y = pack2(x[4 * i + 2] * rs * g4.z * sigmoidf_(lo16(o.y)), x[4 * i + 3] * rs * g4.w * sigmoidf_(hi16(o.y)));
;         ((uint2*)(Hf + ro))[i] = w_;
;       }
.LBB0_371:
	v_lshl_add_u64 v[30:31], v[28:29], 0, v[0:1]
	s_mov_b64 s[2:3], 0x2f618100
	v_add_co_u32_e32 v32, vcc, 0x2f618000, v30
	v_lshl_add_u64 v[34:35], v[30:31], 0, s[2:3]
	s_nop 0
	v_addc_co_u32_e32 v33, vcc, 0, v31, vcc
	global_load_dwordx4 v[46:49], v[32:33], off offset:256
	global_load_dwordx2 v[58:59], v[34:35], off offset:16
	v_add_co_u32_e32 v34, vcc, 0x32c18000, v30
	s_mov_b64 s[2:3], 0x32c18100
	s_nop 0
	v_addc_co_u32_e32 v35, vcc, 0, v31, vcc
	v_lshl_add_u64 v[36:37], v[30:31], 0, s[2:3]
	global_load_dwordx4 v[54:57], v[34:35], off offset:256
	global_load_dwordx2 v[60:61], v[36:37], off offset:16
	v_lshl_add_u64 v[34:35], v[26:27], 0, v[0:1]
	s_mov_b32 s1, 0x1afd9000
	v_add_co_u32_e32 v34, vcc, s1, v34
	s_mov_b32 s1, 0x800000
	s_nop 0
	v_addc_co_u32_e32 v35, vcc, 0, v35, vcc
	global_load_dwordx2 v[50:51], v[34:35], off offset:768
	global_load_dwordx2 v[100:101], v[34:35], off offset:776
	global_load_dwordx2 v[102:103], v[34:35], off offset:784
	v_add_co_u32_e32 v122, vcc, 0x36218000, v30
	s_nop 1
	v_addc_co_u32_e32 v123, vcc, 0, v31, vcc
	v_add_co_u32_e32 v124, vcc, 0x39818000, v30
	s_nop 1
	v_addc_co_u32_e32 v125, vcc, 0, v31, vcc
	v_add_co_u32_e32 v126, vcc, 0x28a18000, v30
	s_nop 1
	v_addc_co_u32_e32 v127, vcc, 0, v31, vcc
	global_load_dwordx2 v[104:105], v[122:123], off offset:256
	global_load_dwordx2 v[106:107], v[124:125], off offset:256
	global_load_dwordx2 v[108:109], v[126:127], off offset:256
	global_load_dwordx2 v[110:111], v[122:123], off offset:264
	global_load_dwordx2 v[112:113], v[124:125], off offset:264
	global_load_dwordx2 v[114:115], v[126:127], off offset:264
	global_load_dwordx2 v[116:117], v[122:123], off offset:272
	global_load_dwordx2 v[118:119], v[124:125], off offset:272
	global_load_dwordx2 v[120:121], v[126:127], off offset:272
	s_waitcnt vmcnt(15)
	v_lshlrev_b32_e32 v36, 16, v46
	v_and_b32_e32 v37, 0xffff0000, v46
	v_lshlrev_b32_e32 v38, 16, v47
	v_and_b32_e32 v39, 0xffff0000, v47
	v_lshlrev_b32_e32 v46, 16, v48
	v_and_b32_e32 v47, 0xffff0000, v48
	s_waitcnt vmcnt(13)
	v_lshlrev_b32_e32 v40, 16, v54
	v_and_b32_e32 v41, 0xffff0000, v54
	v_pk_add_f32 v[40:41], v[36:37], v[40:41]
	v_lshlrev_b32_e32 v42, 16, v55
	v_and_b32_e32 v43, 0xffff0000, v55
	v_pk_add_f32 v[38:39], v[38:39], v[42:43]
	v_pk_add_f32 v[42:43], v[40:41], v[40:41] op_sel:[0,1] op_sel_hi:[1,0]
	v_lshlrev_b32_e32 v44, 16, v56
	v_pk_add_f32 v[68:69], v[38:39], v[42:43]
	s_waitcnt vmcnt(11)
	v_lshlrev_b32_e32 v48, 16, v50
	v_mul_f32_e32 v48, 0xbfb8aa3b, v48
	v_exp_f32_e32 v52, v48
	v_and_b32_e32 v48, 0xffff0000, v50
	v_mul_f32_e32 v48, 0xbfb8aa3b, v48
	v_exp_f32_e32 v53, v48
	v_lshlrev_b32_e32 v48, 16, v51
	v_mul_f32_e32 v48, 0xbfb8aa3b, v48
	v_exp_f32_e32 v54, v48
	v_and_b32_e32 v48, 0xffff0000, v51
	v_mul_f32_e32 v48, 0xbfb8aa3b, v48
	v_pk_add_f32 v[36:37], v[52:53], 1.0 op_sel_hi:[1,0]
	v_exp_f32_e32 v55, v48
	s_nop 0
	v_rcp_f32_e32 v37, v37
	v_lshlrev_b32_e32 v42, 16, v49
	v_lshlrev_b32_e32 v43, 16, v58
	v_pk_add_f32 v[54:55], v[54:55], 1.0 op_sel_hi:[1,0]
	v_rcp_f32_e32 v36, v36
	v_and_b32_e32 v45, 0xffff0000, v56
	v_and_b32_e32 v56, 0xffff0000, v57
	v_pk_add_f32 v[44:45], v[46:47], v[44:45]
	v_lshlrev_b32_e32 v50, 16, v57
	v_lshlrev_b32_e32 v51, 16, v60
	v_pk_add_f32 v[42:43], v[42:43], v[50:51]
	v_and_b32_e32 v51, 0xffff0000, v58
	v_and_b32_e32 v48, 0xffff0000, v49
	v_lshlrev_b32_e32 v49, 16, v59
	v_and_b32_e32 v50, 0xffff0000, v59
	v_pk_add_f32 v[58:59], v[38:39], v[68:69] op_sel:[1,0] op_sel_hi:[0,1]
	v_mov_b32_e32 v59, v50
	v_rcp_f32_e32 v55, v55
	v_lshlrev_b32_e32 v57, 16, v61
	v_pk_add_f32 v[48:49], v[48:49], v[56:57]
	v_and_b32_e32 v57, 0xffff0000, v61
	v_mov_b32_e32 v56, v1
	v_and_b32_e32 v53, 0xffff0000, v60
	v_pk_add_f32 v[60:61], v[58:59], v[56:57]
	v_rcp_f32_e32 v54, v54
	v_mov_b32_e32 v57, v49
	v_mov_b32_e32 v56, v61
	v_mov_b32_e32 v50, v44
	v_mov_b32_e32 v52, v45
	v_pk_add_f32 v[46:47], v[50:51], v[52:53]
	v_mov_b32_e32 v59, v48
	v_pk_add_f32 v[50:51], v[42:43], v[46:47]
	v_mov_b32_e32 v58, v42
	v_pk_add_f32 v[48:49], v[48:49], v[50:51]
	s_nop 0
	v_pk_add_f32 v[48:49], v[60:61], v[48:49]
	s_nop 0
	v_add_f32_e32 v42, v48, v49
	ds_bpermute_b32 v46, v63, v42
	s_waitcnt lgkmcnt(0)
	v_add_f32_e32 v42, v42, v46
	ds_bpermute_b32 v46, v64, v42
	s_waitcnt lgkmcnt(0)
	v_add_f32_e32 v42, v42, v46
	ds_bpermute_b32 v46, v65, v42
	s_waitcnt lgkmcnt(0)
	v_add_f32_e32 v42, v42, v46
	ds_bpermute_b32 v46, v66, v42
	s_waitcnt lgkmcnt(0)
	v_add_f32_e32 v42, v42, v46
	v_mul_f32_e32 v42, 0x3baaaaab, v42
	v_pk_add_f32 v[48:49], v[40:41], v[42:43] op_sel_hi:[1,0] neg_lo:[0,1] neg_hi:[0,1]
	v_pk_add_f32 v[52:53], v[38:39], v[42:43] op_sel_hi:[1,0] neg_lo:[0,1] neg_hi:[0,1]
	v_pk_mul_f32 v[50:51], v[48:49], v[48:49]
	v_mov_b32_e32 v46, v43
	v_pk_mul_f32 v[60:61], v[52:53], v[52:53]
	v_pk_add_f32 v[40:41], v[46:47], v[42:43] op_sel_hi:[1,0] neg_lo:[0,1] neg_hi:[0,1]
	v_add_f32_e32 v46, v50, v51
	v_pk_add_f32 v[68:69], v[44:45], v[42:43] op_sel_hi:[1,0] neg_lo:[0,1] neg_hi:[0,1]
	v_add_f32_e32 v46, v60, v46
	v_pk_mul_f32 v[70:71], v[68:69], v[68:69]
	v_add_f32_e32 v46, v61, v46
	v_pk_add_f32 v[44:45], v[58:59], v[42:43] op_sel_hi:[1,0] neg_lo:[0,1] neg_hi:[0,1]
	v_add_f32_e32 v46, v70, v46
	v_pk_mul_f32 v[58:59], v[44:45], v[44:45]
	v_add_f32_e32 v46, v71, v46
	v_add_f32_e32 v46, v58, v46
	v_pk_add_f32 v[38:39], v[56:57], v[42:43] op_sel_hi:[1,0] neg_lo:[0,1] neg_hi:[0,1]
	v_pk_mul_f32 v[42:43], v[40:41], v[40:41]
	v_add_f32_e32 v46, v59, v46
	v_add_f32_e32 v42, v42, v46
	v_pk_mul_f32 v[56:57], v[38:39], v[38:39]
	v_add_f32_e32 v42, v43, v42
	v_add_f32_e32 v42, v57, v42
	v_add_f32_e32 v42, v56, v42
	ds_bpermute_b32 v43, v63, v42
	s_waitcnt lgkmcnt(0)
; DI unsigned pack2(float a, float b) { f32x2_t v = {a, b}; bf16x2_t r = __builtin_convertvector(v, bf16x2_t); return __builtin_bit_cast(unsigned, r); }
; DI float lo16(unsigned u) { return __uint_as_float(u << 16); }
; DI float hi16(unsigned u) { return __uint_as_float(u & 0xffff0000u); }
; DI float sigmoidf_(float x) { return 1.f / (1.f + __expf(-x)); }
; DI void post_scan(const PX& p, int l, int M, unsigned char* smem) {
;     ...
;       const float rs = rsqrtf(q * (1.f / 192.f) + 1e-5f);
;       const uint2* og = (const uint2*)(Zml + (size_t)r * 3072 + 2304 + lane * 12);
;       const float4* gg = (const float4*)(ng + lane * 12);
; #pragma unroll
;       for (int i = 0; i < 3; i++) {
;         const uint2 o = og[i];
;         const float4 g4 = ngv[i];
;         uint2 w_;
;         w_.x = pack2(x[4 * i] * rs * g4.x * sigmoidf_(lo16(o.x)), x[4 * i + 1] * rs * g4.y * sigmoidf_(hi16(o.x)));
;         w_.y = pack2(x[4 * i + 2] * rs * g4.z * sigmoidf_(lo16(o.y)), x[4 * i + 3] * rs * g4.w * sigmoidf_(hi16(o.y)));
;         ((uint2*)(Hf + ro))[i] = w_;
;       }
;     }
;     {
;       const uint2* yf = (const uint2*)(Yf + ro);
;       const uint2* yb = (const uint2*)(Yb + ro);
;       const uint2* zu = (const uint2*)(Zu + ro);
;       const float4* dd = (const float4*)(sd + lane * 12);
; #pragma unroll
;       for (int i = 0; i < 3; i++) {
;         const uint2 a = yf[i], bq = yb[i], u = zu[i];
;         const float4 d4 = sdv[i];
;         float y[4];
;         y[0] = lo16(a.x) + lo16(bq.x) + d4.x * lo16(u.x);
;         y[1] = hi16(a.x) + hi16(bq.x) + d4.y * hi16(u.x);
;         y[2] = lo16(a.y) + lo16(bq.y) + d4.z * lo16(u.y);
;         y[3] = hi16(a.y) + hi16(bq.y) + d4.w * hi16(u.y);
; #pragma unroll
;         for (int j = 0; j < 4; j++) {
;           const float uu = 0.7978845608028654f * (y[j] + 0.044715f * y[j] * y[j] * y[j]);
;           y[j] = 0.5f * y[j] * (1.f + tanhf(uu));
;         }
;         uint2 w_;
;         w_.x = pack2(y[0], y[1]); w_.y = pack2(y[2], y[3]);
;         ((uint2*)(Yf + ro))[i] = w_;
;       }
	v_add_f32_e32 v42, v42, v43
	ds_bpermute_b32 v43, v64, v42
	s_waitcnt lgkmcnt(0)
	v_add_f32_e32 v42, v42, v43
	ds_bpermute_b32 v43, v65, v42
	s_waitcnt lgkmcnt(0)
	v_add_f32_e32 v42, v42, v43
	ds_bpermute_b32 v43, v66, v42
	s_waitcnt lgkmcnt(0)
	v_add_f32_e32 v42, v42, v43
	v_mov_b32_e32 v43, 0x3727c5ac
	v_fmamk_f32 v42, v42, 0x3baaaaab, v43
	v_cmp_gt_f32_e32 vcc, s1, v42
	v_mul_f32_e32 v43, 0x4b800000, v42
	s_mov_b32 s1, 0x36218000
	v_cndmask_b32_e32 v42, v42, v43, vcc
	v_rsq_f32_e32 v42, v42
	s_nop 0
	v_mul_f32_e32 v43, 0x45800000, v42
	v_cndmask_b32_e32 v42, v42, v43, vcc
	v_pk_mul_f32 v[46:47], v[48:49], v[42:43] op_sel_hi:[1,0]
	s_nop 0
	v_pk_mul_f32 v[46:47], v[6:7], v[46:47]
	s_nop 0
	v_pk_mul_f32 v[36:37], v[36:37], v[46:47]
	v_pk_mul_f32 v[46:47], v[52:53], v[42:43] op_sel_hi:[1,0]
	v_cvt_pk_bf16_f32 v36, v36, v37
	v_pk_mul_f32 v[46:47], v[8:9], v[46:47]
	s_nop 0
	v_pk_mul_f32 v[46:47], v[54:55], v[46:47]
	s_nop 0
	v_cvt_pk_bf16_f32 v37, v46, v47
	global_store_dwordx2 v[32:33], v[36:37], off offset:256
	s_waitcnt vmcnt(11)
	v_mov_b64_e32 v[36:37], v[100:101]
	v_lshlrev_b32_e32 v43, 16, v36
	v_and_b32_e32 v36, 0xffff0000, v36
	v_mul_f32_e32 v43, 0xbfb8aa3b, v43
	v_mul_f32_e32 v36, 0xbfb8aa3b, v36
	v_exp_f32_e32 v46, v43
	v_exp_f32_e32 v47, v36
	v_pk_mul_f32 v[48:49], v[68:69], v[42:43] op_sel_hi:[1,0]
	v_pk_add_f32 v[46:47], v[46:47], 1.0 op_sel_hi:[1,0]
	s_nop 0
	v_rcp_f32_e32 v47, v47
	v_pk_mul_f32 v[48:49], v[2:3], v[48:49]
	v_rcp_f32_e32 v46, v46
	s_nop 0
	v_lshlrev_b32_e32 v43, 16, v37
	v_and_b32_e32 v37, 0xffff0000, v37
	v_pk_mul_f32 v[46:47], v[46:47], v[48:49]
	v_mul_f32_e32 v43, 0xbfb8aa3b, v43
	v_mul_f32_e32 v37, 0xbfb8aa3b, v37
	v_cvt_pk_bf16_f32 v36, v46, v47
	v_exp_f32_e32 v46, v43
	v_exp_f32_e32 v47, v37
	v_pk_mul_f32 v[44:45], v[44:45], v[42:43] op_sel_hi:[1,0]
	v_pk_add_f32 v[46:47], v[46:47], 1.0 op_sel_hi:[1,0]
	s_nop 0
	v_rcp_f32_e32 v47, v47
	v_pk_mul_f32 v[44:45], v[4:5], v[44:45]
	v_rcp_f32_e32 v46, v46
	s_nop 0
	v_pk_mul_f32 v[44:45], v[46:47], v[44:45]
	v_pk_mul_f32 v[40:41], v[40:41], v[42:43] op_sel_hi:[1,0]
	v_cvt_pk_bf16_f32 v37, v44, v45
	global_store_dwordx2 v[32:33], v[36:37], off offset:264
	v_pk_mul_f32 v[40:41], v[10:11], v[40:41]
	s_waitcnt vmcnt(11)
	v_mov_b64_e32 v[34:35], v[102:103]
	v_lshlrev_b32_e32 v36, 16, v34
	v_and_b32_e32 v34, 0xffff0000, v34
	v_mul_f32_e32 v36, 0xbfb8aa3b, v36
	v_mul_f32_e32 v34, 0xbfb8aa3b, v34
	v_exp_f32_e32 v36, v36
	v_exp_f32_e32 v37, v34
	s_nop 0
	v_pk_add_f32 v[36:37], v[36:37], 1.0 op_sel_hi:[1,0]
	s_nop 0
	v_rcp_f32_e32 v37, v37
	v_rcp_f32_e32 v36, v36
	s_nop 0
	v_pk_mul_f32 v[36:37], v[36:37], v[40:41]
	v_pk_mul_f32 v[38:39], v[38:39], v[42:43] op_sel_hi:[1,0]
	v_cvt_pk_bf16_f32 v34, v36, v37
	v_lshlrev_b32_e32 v36, 16, v35
	v_and_b32_e32 v35, 0xffff0000, v35
	v_mul_f32_e32 v36, 0xbfb8aa3b, v36
	v_mul_f32_e32 v35, 0xbfb8aa3b, v35
	v_exp_f32_e32 v36, v36
	v_exp_f32_e32 v37, v35
	v_pk_mul_f32 v[38:39], v[12:13], v[38:39] op_sel:[0,1] op_sel_hi:[1,0]
	v_pk_add_f32 v[36:37], v[36:37], 1.0 op_sel_hi:[1,0]
	s_nop 0
	v_rcp_f32_e32 v37, v37
	v_rcp_f32_e32 v36, v36
	s_nop 0
	v_pk_mul_f32 v[36:37], v[36:37], v[38:39]
	s_nop 0
	v_cvt_pk_bf16_f32 v35, v36, v37
	global_store_dwordx2 v[32:33], v[34:35], off offset:272
	v_add_co_u32_e32 v32, vcc, s1, v30
	s_mov_b32 s1, 0x39818000
	s_nop 0
	v_addc_co_u32_e32 v33, vcc, 0, v31, vcc
	v_add_co_u32_e32 v34, vcc, s1, v30
	s_mov_b32 s1, 0x28a18000
	s_nop 0
	v_addc_co_u32_e32 v35, vcc, 0, v31, vcc
	v_add_co_u32_e32 v36, vcc, s1, v30
	v_addc_co_u32_e32 v37, vcc, 0, v31, vcc
	s_mov_b32 s1, 0x3f200000
	s_waitcnt vmcnt(11)
	v_mov_b64_e32 v[38:39], v[104:105]
	v_lshlrev_b32_e32 v44, 16, v38
	s_waitcnt vmcnt(10)
	v_mov_b64_e32 v[40:41], v[106:107]
	v_lshlrev_b32_e32 v45, 16, v40
	v_add_f32_e32 v44, v45, v44
	s_waitcnt vmcnt(9)
	v_mov_b64_e32 v[42:43], v[108:109]
	v_lshlrev_b32_e32 v45, 16, v42
	v_fmac_f32_e32 v44, v14, v45
	v_mul_f32_e32 v45, 0x3d372713, v44
	v_mul_f32_e32 v45, v44, v45
	v_fma_f32 v45, v44, v45, v44
	v_mul_f32_e32 v45, 0x3f4c422a, v45
	v_cmp_nlt_f32_e64 s[2:3], |v45|, s1
	s_and_saveexec_b64 s[12:13], s[2:3]
	s_xor_b64 s[12:13], exec, s[12:13]
	s_cbranch_execz .LBB0_373
	v_add_f32_e64 v46, |v45|, |v45|
	v_mul_f32_e32 v47, 0x3fb8aa3b, v46
	v_rndne_f32_e32 v48, v47
	s_mov_b32 s2, 0x3fb8aa3b
	v_sub_f32_e32 v49, v47, v48
	v_fma_f32 v47, v46, s2, -v47
	v_fmac_f32_e32 v47, 0x32a5705f, v46
	v_add_f32_e32 v47, v49, v47
	v_cvt_i32_f32_e32 v48, v48
	v_exp_f32_e32 v47, v47
	s_mov_b32 s2, 0xc2ce8ed0
	v_cmp_ngt_f32_e32 vcc, s2, v46
	s_mov_b32 s2, 0x42b17218
	v_ldexp_f32 v47, v47, v48
	v_cndmask_b32_e32 v47, 0, v47, vcc
	v_cmp_nlt_f32_e32 vcc, s2, v46
	s_nop 1
	v_cndmask_b32_e32 v46, v212, v47, vcc
	v_add_f32_e32 v46, 1.0, v46
	v_rcp_f32_e32 v46, v46
	s_nop 0
	v_fma_f32 v46, v46, -2.0, 1.0

; DI unsigned pack2(float a, float b) { f32x2_t v = {a, b}; bf16x2_t r = __builtin_convertvector(v, bf16x2_t); return __builtin_bit_cast(unsigned, r); }
; DI void mlstm_job(const PX& p, int l, int job, unsigned char* smem) {
;     ...
;       if (w < 6) {
; #pragma unroll
;         for (int ti = 0; ti < 2; ti++) {
;           const int tl = ti * 32 + lr;
;           const float dn = fmaxf(fabsf(denA[tl]), emtA[par * 64 + tl]);
;           const float inv = 1.f / dn;
;           const int pos = c * 64 + tl;
;           const int t = dir ? Lseg - 1 - pos : pos;
;           bfu* dst = H + (size_t)(tokbase + t) * 768 + h * 192 + 32 * w + 4 * lh;
; #pragma unroll
;           for (int g4 = 0; g4 < 4; g4++) {
;             uint2 o;
;             o.x = pack2(num[ti][4 * g4] * inv, num[ti][4 * g4 + 1] * inv);
;             o.y = pack2(num[ti][4 * g4 + 2] * inv, num[ti][4 * g4 + 3] * inv);
;             *(uint2*)(dst + 8 * g4) = o;
;           }
;         }
;       }
.LBB0_462:
	s_or_b64 exec, exec, s[62:63]
	s_barrier
	s_mov_b64 s[62:63], exec
	v_readlane_b32 s0, v255, 27
	v_readlane_b32 s1, v255, 28
	s_and_b64 s[0:1], s[62:63], s[0:1]
	s_mov_b64 exec, s[0:1]
	s_cbranch_execz .LBB0_448
	v_add_u32_e32 v2, s27, v251
	ds_read_b32 v0, v189
	ds_read2_b32 v[2:3], v2 offset1:32
	s_waitcnt lgkmcnt(1)
	v_max_f32_e64 v0, |v0|, |v0|
	s_waitcnt lgkmcnt(0)
	v_max_f32_e32 v2, v2, v2
	v_max_f32_e32 v0, v0, v2
	v_rcp_f32_e32 v0, v0
	s_nop 0
	v_or_b32_e32 v2, s26, v176
	v_xad_u32 v4, v2, -1, s69
	v_cndmask_b32_e64 v2, v4, v2, s[4:5]
	v_add_u32_e32 v2, s61, v2
	v_pk_mul_f32 v[6:7], v[128:129], v[0:1] op_sel_hi:[1,0]
	v_pk_mul_f32 v[8:9], v[130:131], v[0:1] op_sel_hi:[1,0]
	v_mad_i64_i32 v[4:5], s[0:1], v2, s81, v[166:167]
	v_cvt_pk_bf16_f32 v6, v6, v7
	v_cvt_pk_bf16_f32 v7, v8, v9
	global_store_dwordx2 v[4:5], v[6:7], off
	v_pk_mul_f32 v[6:7], v[132:133], v[0:1] op_sel_hi:[1,0]
	v_pk_mul_f32 v[8:9], v[134:135], v[0:1] op_sel_hi:[1,0]
	v_cvt_pk_bf16_f32 v6, v6, v7
	v_cvt_pk_bf16_f32 v7, v8, v9
	global_store_dwordx2 v[4:5], v[6:7], off offset:16
	v_pk_mul_f32 v[6:7], v[136:137], v[0:1] op_sel_hi:[1,0]
	v_pk_mul_f32 v[8:9], v[138:139], v[0:1] op_sel_hi:[1,0]
	v_cvt_pk_bf16_f32 v6, v6, v7
	v_cvt_pk_bf16_f32 v7, v8, v9
	global_store_dwordx2 v[4:5], v[6:7], off offset:32
	v_pk_mul_f32 v[6:7], v[140:141], v[0:1] op_sel_hi:[1,0]
	v_pk_mul_f32 v[8:9], v[142:143], v[0:1] op_sel_hi:[1,0]
	ds_read_b32 v0, v250
	v_max_f32_e32 v2, v3, v3
	v_cvt_pk_bf16_f32 v6, v6, v7
	v_cvt_pk_bf16_f32 v7, v8, v9
	global_store_dwordx2 v[4:5], v[6:7], off offset:48
	s_waitcnt lgkmcnt(0)
	v_max_f32_e64 v0, |v0|, |v0|
	v_max_f32_e32 v0, v0, v2
	v_rcp_f32_e32 v0, v0
	s_nop 0
	v_or_b32_e32 v2, s26, v249
	v_xad_u32 v3, v2, -1, s69
	v_cndmask_b32_e64 v2, v3, v2, s[4:5]
	v_add_u32_e32 v2, s61, v2
	v_pk_mul_f32 v[4:5], v[112:113], v[0:1] op_sel_hi:[1,0]
	v_pk_mul_f32 v[6:7], v[114:115], v[0:1] op_sel_hi:[1,0]
	v_mad_i64_i32 v[2:3], s[0:1], v2, s81, v[166:167]
	v_cvt_pk_bf16_f32 v4, v4, v5
	v_cvt_pk_bf16_f32 v5, v6, v7
	global_store_dwordx2 v[2:3], v[4:5], off
	v_pk_mul_f32 v[4:5], v[116:117], v[0:1] op_sel_hi:[1,0]
	v_pk_mul_f32 v[6:7], v[118:119], v[0:1] op_sel_hi:[1,0]
	v_cvt_pk_bf16_f32 v4, v4, v5
	v_cvt_pk_bf16_f32 v5, v6, v7
	global_store_dwordx2 v[2:3], v[4:5], off offset:16
	v_pk_mul_f32 v[4:5], v[120:121], v[0:1] op_sel_hi:[1,0]
	v_pk_mul_f32 v[6:7], v[122:123], v[0:1] op_sel_hi:[1,0]
	v_cvt_pk_bf16_f32 v4, v4, v5
	v_cvt_pk_bf16_f32 v5, v6, v7
	global_store_dwordx2 v[2:3], v[4:5], off offset:32
	v_pk_mul_f32 v[4:5], v[124:125], v[0:1] op_sel_hi:[1,0]
	v_pk_mul_f32 v[6:7], v[126:127], v[0:1] op_sel_hi:[1,0]
	v_cvt_pk_bf16_f32 v4, v4, v5
	v_cvt_pk_bf16_f32 v5, v6, v7
	global_store_dwordx2 v[2:3], v[4:5], off offset:48
	s_branch .LBB0_448

; #define OPAQUE(x) asm volatile("" : "+v"(x))
; #define TIDX(p) ((p).wv * 64 + (int)__builtin_amdgcn_mbcnt_hi(~0u, __builtin_amdgcn_mbcnt_lo(~0u, 0u)))
; DI void s5_job(const PX& p, int l, int job, unsigned char* smem) {
;   int tid_ = TIDX(p); OPAQUE(tid_); const int tid = tid_, lane = tid & 63, w = tid >> 6;
;   const bool active = w < 4;
;   const int cl = (w >> 1) & 1, hf = w & 1;
;   const int chain = job * 2 + cl;
;   const int g = chain >> 1, dir = chain & 1;
;   const int b = lane & 15, kq = lane >> 4;
;   const int pg = (l * 2 + dir) * 48 + g;
;   const float* a_re = p.in[21] + (size_t)pg * 64;
;   const float* a_im = p.in[22] + (size_t)pg * 64;
;   const float dt = expf(p.in[23][pg]);
;   const float* b_re = p.in[24] + (size_t)pg * 1024;
;   const float* b_im = p.in[25] + (size_t)pg * 1024;
;   const float* c_re = p.in[26] + (size_t)pg * 1024;
;   const float* c_im = p.in[27] + (size_t)pg * 1024;
;   float* ex = (float*)smem + cl * (2 * 32 * 64);
;   bf16x8 Are[2], Aim[2], Cf[2];
;   float lre[2][4], lim[2][4];
; #pragma unroll
;   for (int tt = 0; tt < 2; tt++) {
;     const int tau = 2 * hf + tt;
;     {
;       const int pp = 16 * tau + (lane & 15);
;       const float ar = a_re[pp], ai = a_im[pp];
;       const float mag = expf(dt * ar);
;       float sn0, cs0; sincos_f(dt * ai, sn0, cs0);
;       const float abr = mag * cs0, abi = mag * sn0;
;       const float den = ar * ar + ai * ai;
;       const float cor = ((abr - 1.f) * ar + abi * ai) / den;
;       const float coi = (abi * ar - (abr - 1.f) * ai) / den;
; #pragma unroll
;       for (int j = 0; j < 8; j++) {
;         float vr = 0.f, vi = 0.f;
;         if (kq < 2) {
;           const float br = b_re[pp * 16 + 8 * kq + j], bi = b_im[pp * 16 + 8 * kq + j];
;           vr = cor * br - coi * bi;
;           vi = cor * bi + coi * br;
;         }
;         Are[tt][j] = (short)f2bf(vr);
;         Aim[tt][j] = (short)f2bf(vi);
;       }
;     }
.LBB0_465:
	s_and_b64 vcc, exec, s[4:5]
	s_cbranch_vccz .LBB0_425
	s_waitcnt vmcnt(0)
	v_mov_b32_e32 v12, v188
	v_mov_b32_e32 v0, s38
	v_bfe_u32 v40, v12, 7, 1
	v_or_b32_e32 v2, s41, v40
	s_waitcnt lgkmcnt(0)
	v_mad_u64_u32 v[4:5], s[0:1], v2, 48, v[0:1]
	v_ashrrev_i32_e32 v5, 31, v4
	v_readlane_b32 s0, v252, 35
	v_lshlrev_b64 v[6:7], 8, v[4:5]
	v_readlane_b32 s10, v252, 45
	v_readlane_b32 s11, v252, 46
	v_readlane_b32 s12, v252, 47
	v_readlane_b32 s13, v252, 48
	v_readlane_b32 s14, v252, 49
	v_readlane_b32 s15, v252, 50
	v_lshl_add_u64 v[28:29], s[10:11], 0, v[6:7]
	v_lshl_add_u64 v[32:33], s[12:13], 0, v[6:7]
	v_lshl_add_u64 v[6:7], v[4:5], 2, s[14:15]
	global_load_dword v0, v[6:7], off
	s_mov_b32 s16, 0x3fb8aa3b
	v_ashrrev_i32_e32 v41, 6, v12
	v_and_b32_e32 v38, 1, v41
	v_and_b32_e32 v39, 15, v12
	s_mov_b32 s17, 0xc2ce8ed0
	v_lshlrev_b32_e32 v30, 5, v38
	s_mov_b32 s18, 0x42b17218
	v_or_b32_e32 v14, v30, v39
	v_readlane_b32 s1, v252, 36
	v_readlane_b32 s2, v252, 37
	v_readlane_b32 s3, v252, 38
	v_readlane_b32 s4, v252, 39
	v_readlane_b32 s5, v252, 40
	v_readlane_b32 s6, v252, 41
	v_readlane_b32 s7, v252, 42
	v_readlane_b32 s8, v252, 43
	v_readlane_b32 s9, v252, 44
	v_readlane_b32 s0, v252, 51
	v_lshlrev_b64 v[8:9], 12, v[4:5]
	v_readlane_b32 s1, v252, 52
	v_bfe_u32 v16, v12, 4, 2
	v_lshlrev_b32_e32 v42, 3, v16
	v_and_b32_e32 v3, 63, v12
	v_readlane_b32 s2, v252, 53
	v_readlane_b32 s3, v252, 54
	v_readlane_b32 s4, v252, 55
	v_readlane_b32 s5, v252, 56
	v_readlane_b32 s8, v252, 59
	v_readlane_b32 s6, v252, 57
	v_readlane_b32 s7, v252, 58
	v_cmp_gt_u32_e64 s[4:5], 32, v3
	s_mov_b32 s8, 0x42b17218
	v_readlane_b32 s9, v252, 60
	v_readlane_b32 s10, v252, 61
	v_readlane_b32 s11, v252, 62
	v_readlane_b32 s12, v252, 63
	v_readlane_b32 s13, v253, 0
	v_readlane_b32 s14, v253, 1
	v_readlane_b32 s15, v253, 2
	s_waitcnt vmcnt(0)
	v_mul_f32_e32 v2, 0x3fb8aa3b, v0
	v_fma_f32 v6, v0, s16, -v2
	v_rndne_f32_e32 v7, v2
	v_fmac_f32_e32 v6, 0x32a5705f, v0
	v_sub_f32_e32 v2, v2, v7
	v_add_f32_e32 v2, v2, v6
	v_exp_f32_e32 v2, v2
	v_cvt_i32_f32_e32 v6, v7
	v_cmp_ngt_f32_e32 vcc, s17, v0
	v_ldexp_f32 v2, v2, v6
	s_nop 0
	v_cndmask_b32_e32 v2, 0, v2, vcc
	v_cmp_nlt_f32_e32 vcc, s18, v0
	v_lshlrev_b32_e32 v0, 2, v14
	v_lshl_add_u64 v[10:11], v[28:29], 0, v[0:1]
	global_load_dword v10, v[10:11], off
	v_lshl_add_u64 v[18:19], v[32:33], 0, v[0:1]
	global_load_dword v11, v[18:19], off
	v_cndmask_b32_e32 v2, v212, v2, vcc
	v_mov_b32_e32 v19, 0x3c08839e
	v_lshl_add_u64 v[6:7], s[0:1], 0, v[8:9]
	v_lshl_add_u64 v[8:9], s[2:3], 0, v[8:9]
	s_mov_b32 s2, 0x3fb8aa3b
	s_mov_b32 s3, 0xc2ce8ed0
	s_waitcnt vmcnt(1)
	v_mul_f32_e32 v0, v2, v10
	v_mul_f32_e32 v13, 0x3fb8aa3b, v0
	v_fma_f32 v15, v0, s16, -v13
	v_rndne_f32_e32 v17, v13
	v_fmac_f32_e32 v15, 0x32a5705f, v0
	v_sub_f32_e32 v13, v13, v17
	v_add_f32_e32 v13, v13, v15
	v_exp_f32_e32 v13, v13
	v_cvt_i32_f32_e32 v15, v17
	v_cmp_ngt_f32_e32 vcc, s17, v0
	v_ldexp_f32 v13, v13, v15
	s_waitcnt vmcnt(0)
	v_mul_f32_e32 v15, v2, v11
	v_cndmask_b32_e32 v13, 0, v13, vcc
	v_cmp_nlt_f32_e32 vcc, s18, v0
	v_mul_f32_e32 v0, 0x3f22f983, v15
	v_rndne_f32_e32 v0, v0
	v_fmac_f32_e32 v15, 0xbfc90000, v0
	v_fmac_f32_e32 v15, 0xb9fda000, v0
	v_fmac_f32_e32 v15, 0xb3a22169, v0
	v_cvt_i32_f32_e32 v17, v0
	v_mul_f32_e32 v0, v15, v15
	v_fmamk_f32 v19, v0, 0xb94ca1f9, v19
	v_mul_f32_e32 v18, v15, v0
	v_fmaak_f32 v19, v0, v19, 0xbe2aaaa3
	v_fmac_f32_e32 v15, v18, v19
	v_mov_b32_e32 v18, 0xbab6061a
	v_fmamk_f32 v187, v0, 0x37ccf5ce, v18
	v_pk_mul_f32 v[18:19], v[0:1], v[186:187] op_sel_hi:[0,1]
	v_mul_f32_e32 v20, v0, v0
	v_add_f32_e32 v0, 0x3d2aaaa5, v19
	v_sub_f32_e32 v18, 1.0, v18
	v_fmac_f32_e32 v18, v20, v0
	v_and_b32_e32 v0, 1, v17
	v_cndmask_b32_e32 v13, v212, v13, vcc
	v_cmp_eq_u32_e32 vcc, 0, v0
	v_pk_mul_f32 v[20:21], v[10:11], v[10:11]
	s_nop 0
	v_cndmask_b32_e32 v0, v18, v15, vcc
	v_cndmask_b32_e32 v15, v15, v18, vcc
	v_and_b32_e32 v18, 2, v17
	v_add_u32_e32 v17, 1, v17
	v_cmp_eq_u32_e32 vcc, 0, v18
	v_and_b32_e32 v17, 2, v17
	s_nop 0
	v_cndmask_b32_e64 v0, -v0, v0, vcc
	v_cmp_eq_u32_e32 vcc, 0, v17
	v_mul_f32_e32 v18, v13, v0
	v_mov_b32_e32 v0, v11
	v_cndmask_b32_e64 v15, -v15, v15, vcc
	v_fma_f32 v19, v13, v15, -1.0
	v_pk_mul_f32 v[22:23], v[0:1], v[18:19] op_sel:[0,1] op_sel_hi:[0,0]
	v_pk_fma_f32 v[24:25], v[10:11], v[18:19], v[22:23] neg_lo:[0,0,1] neg_hi:[0,0,1]
	v_pk_fma_f32 v[10:11], v[10:11], v[18:19], v[22:23] op_sel_hi:[0,1,1]
	v_pk_add_f32 v[18:19], v[20:21], v[20:21] op_sel:[0,1] op_sel_hi:[0,1]
	v_rcp_f32_e32 v10, v19
	s_nop 0
	v_mul_f32_e32 v11, v11, v10
	v_rcp_f32_e32 v10, v18
	s_nop 0
	v_mul_f32_e32 v10, v24, v10
	v_lshl_add_u32 v0, v14, 4, v42
	v_mov_b32_e32 v13, 0
	v_lshlrev_b32_e32 v0, 2, v0
	v_mov_b32_e32 v15, 0
	s_and_saveexec_b64 s[6:7], s[4:5]
	s_cbranch_execz .LBB0_468
	v_lshl_add_u64 v[18:19], v[6:7], 0, v[0:1]
	v_lshl_add_u64 v[20:21], v[8:9], 0, v[0:1]
	global_load_dword v20, v[20:21], off
	s_nop 0
	global_load_dword v18, v[18:19], off
	s_waitcnt vmcnt(1)
	v_pk_mul_f32 v[20:21], v[10:11], v[20:21] op_sel_hi:[1,0]
	s_waitcnt vmcnt(0)
	v_pk_fma_f32 v[22:23], v[10:11], v[18:19], v[20:21] op_sel:[1,0,0] op_sel_hi:[0,0,1]
	v_pk_fma_f32 v[18:19], v[10:11], v[18:19], v[20:21] op_sel:[1,0,0] op_sel_hi:[0,0,1] neg_lo:[0,0,1] neg_hi:[0,0,1]
	v_cvt_pk_bf16_f32 v15, v18, v23
